# gla_combine loops software-pipelined one row ahead with dwordx4 loads
# speedup vs baseline: 1.0037x; 1.0037x over previous
.LBB0_88:
	s_cmp_eq_u32 s2, 10
	s_cselect_b64 s[0:1], -1, 0
	s_cmp_gt_i32 s48, 0
	v_writelane_b32 v249, s2, 56
	s_cselect_b64 s[2:3], -1, 0
	s_and_b64 s[0:1], s[0:1], s[2:3]
	s_andn2_b64 vcc, exec, s[0:1]
	s_lshl_b32 s6, s48, 8
	s_cbranch_vccnz .LBB0_93
	v_mov_b32_e32 v6, v179
	v_readlane_b32 s0, v251, 54
	v_ashrrev_i32_e32 v0, 6, v6
	s_nop 0
	v_add_u32_e32 v4, s0, v0
	s_mov_b32 s0, 0x8000
	v_cmp_gt_i32_e32 vcc, s0, v4
	s_and_saveexec_b64 s[0:1], vcc
	v_readlane_b32 s20, v253, 19
	v_readlane_b32 s22, v253, 21
	v_readlane_b32 s21, v253, 20
	v_readlane_b32 s23, v253, 22
	s_mov_b32 s24, 0x800000
	s_cbranch_execz .LBB0_92
	s_add_i32 s94, s6, 0xffffff00
	s_mov_b32 s26, s6
	v_readlane_b32 s4, v250, 26
	s_lshl_b64 s[2:3], s[94:95], 2
	v_readlane_b32 s16, v250, 38
	v_readlane_b32 s17, v250, 39
	s_add_u32 s2, s16, s2
	v_lshlrev_b32_e32 v0, 4, v6
	s_addc_u32 s3, s17, s3
	v_and_b32_e32 v0, 0x3f0, v0
	global_load_dwordx4 v[0:3], v0, s[2:3]
	v_cmp_lt_i32_e32 vcc, v205, v204
	v_and_b32_e32 v16, 63, v6
	v_readlane_b32 s6, v250, 28
	v_cndmask_b32_e32 v5, v203, v205, vcc
	v_cmp_lt_i32_e32 vcc, v206, v204
	v_lshlrev_b32_e32 v10, 2, v5
	s_mov_b64 s[2:3], 0x8988000
	v_cndmask_b32_e32 v5, v203, v206, vcc
	v_cmp_lt_i32_e32 vcc, v207, v204
	v_lshlrev_b32_e32 v11, 2, v5
	s_mov_b32 s6, s26
	v_cndmask_b32_e32 v5, v203, v207, vcc
	v_cmp_lt_i32_e32 vcc, v208, v204
	v_lshlrev_b32_e32 v12, 2, v5
	v_readlane_b32 s5, v250, 27
	v_cndmask_b32_e32 v5, v203, v208, vcc
	v_cmp_lt_i32_e32 vcc, v209, v204
	v_lshlrev_b32_e32 v13, 2, v5
	v_readlane_b32 s7, v250, 29
	v_cndmask_b32_e32 v5, v203, v209, vcc
	v_cmp_lt_i32_e32 vcc, v210, v204
	v_lshlrev_b32_e32 v14, 2, v5
	v_readlane_b32 s8, v250, 30
	v_cndmask_b32_e32 v5, v203, v210, vcc
	v_lshlrev_b32_e32 v15, 2, v5
	v_ashrrev_i32_e32 v5, 31, v4
	v_lshlrev_b64 v[8:9], 11, v[4:5]
	v_lshl_or_b32 v8, v16, 3, v8
	v_lshl_add_u64 v[6:7], s[94:95], 1, v[8:9]
	v_lshlrev_b64 v[8:9], 10, v[4:5]
	s_movk_i32 s94, 0x7fff
	v_lshl_add_u64 v[6:7], v[6:7], 0, s[2:3]
	v_lshl_or_b32 v8, v16, 4, v8
	s_mov_b64 s[2:3], 0
	v_readlane_b32 s9, v250, 31
	v_readlane_b32 s10, v250, 32
	v_readlane_b32 s11, v250, 33
	v_readlane_b32 s12, v250, 34
	v_readlane_b32 s13, v250, 35
	v_readlane_b32 s14, v250, 36
	v_readlane_b32 s15, v250, 37
	v_readlane_b32 s18, v250, 40
	v_readlane_b32 s19, v250, 41
	v_lshl_add_u64 v[42:43], s[46:47], 0, v[8:9]
	v_add_co_u32_e32 v44, vcc, 0x10988000, v42
	s_mov_b64 s[98:99], vcc
	v_add_co_u32_e32 v42, vcc, 0x12988000, v42
	v_addc_co_u32_e64 v45, s[98:99], 0, v43, s[98:99]
	global_load_dwordx4 v[32:35], v[44:45], off sc0 sc1
	v_addc_co_u32_e32 v43, vcc, 0, v43, vcc
	v_lshl_add_u64 v[46:47], s[46:47], 0, v[6:7]
	global_load_dwordx4 v[36:39], v[42:43], off sc0 sc1
	global_load_dwordx2 v[40:41], v[46:47], off sc0 sc1
	s_waitcnt vmcnt(0)
.LBB0_91:
	s_waitcnt vmcnt(1)
	v_mov_b32_e32 v22, v32
	v_mov_b32_e32 v23, v33
	v_mov_b32_e32 v20, v34
	v_mov_b32_e32 v21, v35
	v_mov_b32_e32 v24, v36
	v_mov_b32_e32 v25, v37
	v_mov_b32_e32 v16, v38
	v_mov_b32_e32 v17, v39
	v_mov_b32_e32 v26, v40
	v_mov_b32_e32 v27, v41
	v_lshl_add_u64 v[18:19], s[46:47], 0, v[6:7]
	v_add_u32_e32 v4, s42, v4
	v_cmp_lt_i32_e32 vcc, s94, v4
	s_or_b64 s[2:3], vcc, s[2:3]
	v_lshl_add_u64 v[6:7], v[6:7], 0, s[20:21]
	v_lshl_add_u64 v[8:9], v[8:9], 0, s[22:23]
	s_cbranch_vccnz .Lcmb_nopf_a
	v_lshl_add_u64 v[42:43], s[46:47], 0, v[8:9]
	v_add_co_u32_e32 v44, vcc, 0x10988000, v42
	s_mov_b64 s[98:99], vcc
	v_add_co_u32_e32 v42, vcc, 0x12988000, v42
	v_addc_co_u32_e64 v45, s[98:99], 0, v43, s[98:99]
	global_load_dwordx4 v[32:35], v[44:45], off sc0 sc1
	v_addc_co_u32_e32 v43, vcc, 0, v43, vcc
	v_lshl_add_u64 v[46:47], s[46:47], 0, v[6:7]
	global_load_dwordx4 v[36:39], v[42:43], off sc0 sc1
	global_load_dwordx2 v[40:41], v[46:47], off sc0 sc1
.Lcmb_nopf_a:
	v_pk_add_f32 v[16:17], v[20:21], v[16:17]
	v_pk_add_f32 v[20:21], v[22:23], v[24:25]
	v_pk_mul_f32 v[24:25], v[16:17], v[16:17]
	v_pk_mul_f32 v[22:23], v[20:21], v[20:21]
	v_lshlrev_b32_e32 v5, 16, v26
	v_and_b32_e32 v28, 0xffff0000, v26
	v_lshlrev_b32_e32 v29, 16, v27
	v_and_b32_e32 v30, 0xffff0000, v27
	v_pk_mov_b32 v[26:27], v[22:23], v[24:25] op_sel:[1,0]
	v_mov_b32_e32 v23, v25
	v_pk_add_f32 v[22:23], v[26:27], v[22:23]
	s_nop 0
	v_add_f32_e32 v22, v22, v23
	ds_bpermute_b32 v23, v10, v22
	s_waitcnt lgkmcnt(0)
	v_add_f32_e32 v22, v22, v23
	ds_bpermute_b32 v23, v11, v22
	s_waitcnt lgkmcnt(0)
	v_add_f32_e32 v22, v22, v23
	ds_bpermute_b32 v23, v12, v22
	s_waitcnt lgkmcnt(0)
	v_add_f32_e32 v22, v22, v23
	ds_bpermute_b32 v23, v13, v22
	s_waitcnt lgkmcnt(0)
	v_add_f32_e32 v22, v22, v23
	ds_bpermute_b32 v23, v14, v22
	s_waitcnt lgkmcnt(0)
	v_add_f32_e32 v22, v22, v23
	ds_bpermute_b32 v23, v15, v22
	s_waitcnt lgkmcnt(0)
	v_add_f32_e32 v22, v22, v23
	v_fmamk_f32 v22, v22, 0x3b800000, v178
	v_mul_f32_e32 v23, 0x4b800000, v22
	v_cmp_gt_f32_e32 vcc, s24, v22
	s_nop 1
	v_cndmask_b32_e32 v22, v22, v23, vcc
	v_rsq_f32_e32 v22, v22
	s_nop 0
	v_mul_f32_e32 v23, 0x45800000, v22
	v_cndmask_b32_e32 v22, v22, v23, vcc
	v_mul_f32_e32 v17, v17, v22
	v_mul_f32_e32 v20, v20, v22
	v_mul_f32_e32 v21, v21, v22
	v_mul_f32_e32 v16, v16, v22
	v_mul_f32_e32 v17, v3, v17
	v_mul_f32_e32 v20, v0, v20
	v_mul_f32_e32 v21, v1, v21
	v_mul_f32_e32 v16, v2, v16
	v_mul_f32_e32 v17, v17, v30
	v_mul_f32_e32 v5, v20, v5
	v_mul_f32_e32 v20, v21, v28
	v_mul_f32_e32 v21, v16, v29
	v_cvt_pk_bf16_f32 v16, v5, v20
	v_cvt_pk_bf16_f32 v17, v21, v17
	global_store_dwordx2 v[18:19], v[16:17], off
	s_andn2_b64 exec, exec, s[2:3]
	s_cbranch_execnz .LBB0_91

.LBB0_286:
	v_readlane_b32 s0, v249, 56
	s_cmp_eq_u32 s0, 13
	s_mov_b64 s[0:1], -1
	s_cbranch_scc0 .LBB0_291
	v_mov_b32_e32 v6, v179
	v_readlane_b32 s0, v251, 54
	v_ashrrev_i32_e32 v0, 6, v6
	s_nop 0
	v_add_u32_e32 v4, s0, v0
	s_mov_b32 s0, 0x8000
	v_cmp_gt_i32_e32 vcc, s0, v4
	s_and_saveexec_b64 s[0:1], vcc
	v_readlane_b32 s20, v253, 19
	v_readlane_b32 s22, v253, 21
	v_readlane_b32 s21, v253, 20
	v_readlane_b32 s23, v253, 22
	s_mov_b32 s24, 0x800000
	s_cbranch_execz .LBB0_290
	s_ashr_i32 s7, s6, 31
	s_lshl_b64 s[2:3], s[6:7], 2
	s_mov_b64 s[26:27], s[6:7]
	v_readlane_b32 s4, v250, 26
	v_readlane_b32 s16, v250, 38
	v_readlane_b32 s17, v250, 39
	s_add_u32 s2, s16, s2
	v_lshlrev_b32_e32 v0, 4, v6
	s_addc_u32 s3, s17, s3
	v_and_b32_e32 v0, 0x3f0, v0
	global_load_dwordx4 v[0:3], v0, s[2:3]
	v_cmp_lt_i32_e32 vcc, v205, v204
	v_and_b32_e32 v16, 63, v6
	s_mov_b64 s[2:3], 0x8988000
	v_cndmask_b32_e32 v5, v203, v205, vcc
	v_cmp_lt_i32_e32 vcc, v206, v204
	v_lshlrev_b32_e32 v10, 2, v5
	v_readlane_b32 s5, v250, 27
	v_cndmask_b32_e32 v5, v203, v206, vcc
	v_cmp_lt_i32_e32 vcc, v207, v204
	v_lshlrev_b32_e32 v11, 2, v5
	v_readlane_b32 s6, v250, 28
	v_cndmask_b32_e32 v5, v203, v207, vcc
	v_cmp_lt_i32_e32 vcc, v208, v204
	v_lshlrev_b32_e32 v12, 2, v5
	v_readlane_b32 s7, v250, 29
	v_cndmask_b32_e32 v5, v203, v208, vcc
	v_cmp_lt_i32_e32 vcc, v209, v204
	v_lshlrev_b32_e32 v13, 2, v5
	v_readlane_b32 s8, v250, 30
	v_cndmask_b32_e32 v5, v203, v209, vcc
	v_cmp_lt_i32_e32 vcc, v210, v204
	v_lshlrev_b32_e32 v14, 2, v5
	v_readlane_b32 s9, v250, 31
	v_cndmask_b32_e32 v5, v203, v210, vcc
	v_lshlrev_b32_e32 v15, 2, v5
	v_ashrrev_i32_e32 v5, 31, v4
	v_lshlrev_b64 v[8:9], 11, v[4:5]
	v_lshl_or_b32 v8, v16, 3, v8
	v_lshl_add_u64 v[6:7], s[26:27], 1, v[8:9]
	v_lshlrev_b64 v[8:9], 10, v[4:5]
	v_lshl_add_u64 v[6:7], v[6:7], 0, s[2:3]
	v_lshl_or_b32 v8, v16, 4, v8
	s_mov_b64 s[2:3], 0
	v_readlane_b32 s10, v250, 32
	v_readlane_b32 s11, v250, 33
	v_readlane_b32 s12, v250, 34
	v_readlane_b32 s13, v250, 35
	v_readlane_b32 s14, v250, 36
	v_readlane_b32 s15, v250, 37
	v_readlane_b32 s18, v250, 40
	v_readlane_b32 s19, v250, 41
	v_lshl_add_u64 v[42:43], s[46:47], 0, v[8:9]
	v_add_co_u32_e32 v44, vcc, 0x10988000, v42
	s_mov_b64 s[98:99], vcc
	v_add_co_u32_e32 v42, vcc, 0x12988000, v42
	v_addc_co_u32_e64 v45, s[98:99], 0, v43, s[98:99]
	global_load_dwordx4 v[32:35], v[44:45], off sc0 sc1
	v_addc_co_u32_e32 v43, vcc, 0, v43, vcc
	v_lshl_add_u64 v[46:47], s[46:47], 0, v[6:7]
	global_load_dwordx4 v[36:39], v[42:43], off sc0 sc1
	global_load_dwordx2 v[40:41], v[46:47], off sc0 sc1
	s_waitcnt vmcnt(0)
